# FFN-in paired tiles: shared weight tile double-buffered in the spare 16 KB of LDS so its fill runs under the whole previous k-step
# speedup vs baseline: 1.0609x; 1.0090x over previous
; #define LAS __attribute__((address_space(3)))
; DI int opaque_tid() { int t = threadIdx.x; asm volatile("" : "+v"(t)); return t; }
; DI int lat_tile(int i) { return (i >> 4) * 18 + 2 + (i & 15); }
; template <class Epi>
; DI void gemm_tile(const bf16_t* __restrict__ A, int lda, const bf16_t* __restrict__ Bt, int ldb, int K, int row0, int col0, char* lds, const Epi& epi) {
;   const int tid = opaque_tid(), lane = tid & 63, wid = tid >> 6, wr = wid >> 1, wc = wid & 1, fr = lane & 15, fq = lane >> 4;
;   const bf16_t* ag[4];
;   const bf16_t* bg[4];
; #pragma unroll
;   for (int i = 0; i < 4; ++i) {
;     const int id = i * 256 + tid, r = id >> 3, cp = id & 7, c = cp ^ ((r >> 1) & 7);
;     ag[i] = A + (size_t)(row0 + r) * lda + c * 8;
;     bg[i] = Bt + (size_t)(col0 + r) * ldb + c * 8;
;   }
;   f32x4 acc[4][4];
; #pragma unroll
;   for (int m = 0; m < 4; ++m)
; #pragma unroll
;     for (int n = 0; n < 4; ++n) acc[m][n] = (f32x4){0.f, 0.f, 0.f, 0.f};
;   const int KT = K >> 6;
;   auto stage_a = [&](int kt, int buf) {
;     char* sa = lds + buf * 32768;
; #pragma unroll
;     for (int i = 0; i < 4; ++i)
;       __builtin_amdgcn_global_load_lds((const void __attribute__((address_space(1)))*)(ag[i] + kt * 64), (void LAS*)(sa + (i * 256 + tid) * 16), 16, 0, 0);
;   };
;   auto stage_b = [&](int kt, int buf) {
;     char* sb = lds + buf * 32768 + 16384;
; #pragma unroll
;     for (int i = 0; i < 4; ++i)
;       __builtin_amdgcn_global_load_lds((const void __attribute__((address_space(1)))*)(bg[i] + kt * 64), (void LAS*)(sb + (i * 256 + tid) * 16), 16, 0, 0);
;   };
;   __syncthreads();
;   stage_a(0, 0); stage_b(0, 0);
;   const int swz = fr >> 1;
; template <int KSEL> DI void run_phase(const Params& p, int ph, char* lds) {
;     ...
;       for (int i = 0, tm, tn; xcd_tile(bid, G, i, nm, 44, tm, tn); ++i) gemm_tile(p.HY, DM, p.Wffi, DM, DM, (last ? lat_tile(tm) : tm) * 128, tn * 128, lds, e);
.LBB0_135:
	v_mov_b32_e32 v34, v138
	s_lshl_b32 s2, s28, 7
	v_lshrrev_b32_e32 v35, 4, v34
	v_xor_b32_e32 v1, v35, v34
	v_lshlrev_b32_e32 v1, 4, v1
	s_lshl_b32 s3, s29, 7
	v_and_b32_e32 v110, 0x70, v1
	v_ashrrev_i32_e32 v1, 3, v34
	v_add_u32_e32 v6, s2, v1
	v_add_u32_e32 v10, s3, v1
	v_add_u32_e32 v1, 0x100, v34
	v_readlane_b32 s4, v253, 36
	v_ashrrev_i32_e32 v1, 3, v1
	v_readlane_b32 s8, v253, 40
	v_readlane_b32 s9, v253, 41
	v_ashrrev_i32_e32 v7, 31, v6
	v_add_u32_e32 v14, s2, v1
	v_add_u32_e32 v18, s3, v1
	v_add_u32_e32 v1, 0x200, v34
	s_waitcnt vmcnt(6)
	v_lshlrev_b32_e32 v92, 4, v34
	v_lshl_add_u64 v[2:3], s[8:9], 0, v[110:111]
	v_lshlrev_b64 v[6:7], 11, v[6:7]
	v_ashrrev_i32_e32 v1, 3, v1
	v_readfirstlane_b32 s0, v92
	v_lshl_add_u64 v[8:9], v[2:3], 0, v[6:7]
	v_add_u32_e32 v22, s2, v1
	v_add_u32_e32 v26, s3, v1
	v_add_u32_e32 v1, 0x300, v34
	s_mov_b32 m0, s0
	v_ashrrev_i32_e32 v15, 31, v14
	v_ashrrev_i32_e32 v1, 3, v1
	s_barrier
	global_load_lds_dwordx4 v[8:9], off
	v_add_u32_e32 v8, 0x1000, v92
	v_lshlrev_b64 v[14:15], 11, v[14:15]
	v_ashrrev_i32_e32 v23, 31, v22
	v_add_u32_e32 v30, s2, v1
	v_readfirstlane_b32 s0, v8
	v_add_u32_e32 v8, 0x2000, v92
	v_lshl_add_u64 v[16:17], v[2:3], 0, v[14:15]
	v_lshlrev_b64 v[22:23], 11, v[22:23]
	v_ashrrev_i32_e32 v31, 31, v30
	s_mov_b32 m0, s0
	v_readfirstlane_b32 s0, v8
	v_add_u32_e32 v8, 0x3000, v92
	v_lshl_add_u64 v[24:25], v[2:3], 0, v[22:23]
	v_lshlrev_b64 v[30:31], 11, v[30:31]
	global_load_lds_dwordx4 v[16:17], off
	s_mov_b32 m0, s0
	v_readfirstlane_b32 s0, v8
	v_lshl_add_u64 v[2:3], v[2:3], 0, v[30:31]
	global_load_lds_dwordx4 v[24:25], off
	s_mov_b32 m0, s0
	v_readlane_b32 s5, v253, 37
	v_ashrrev_i32_e32 v11, 31, v10
	global_load_lds_dwordx4 v[2:3], off
	v_add_u32_e32 v2, 0x4000, v92
	v_lshl_add_u64 v[4:5], s[4:5], 0, v[110:111]
	v_lshlrev_b64 v[10:11], 11, v[10:11]
	v_ashrrev_i32_e32 v19, 31, v18
	v_readfirstlane_b32 s0, v2
	v_add_u32_e32 v2, 0x5000, v92
	v_lshl_add_u64 v[12:13], v[4:5], 0, v[10:11]
	v_lshlrev_b64 v[18:19], 11, v[18:19]
	v_ashrrev_i32_e32 v27, 31, v26
	v_add_u32_e32 v32, s3, v1
	s_mov_b32 m0, s0
	v_readfirstlane_b32 s0, v2
	v_add_u32_e32 v2, 0x6000, v92
	v_lshl_add_u64 v[20:21], v[4:5], 0, v[18:19]
	v_lshlrev_b64 v[26:27], 11, v[26:27]
	v_ashrrev_i32_e32 v33, 31, v32
	global_load_lds_dwordx4 v[12:13], off
	s_mov_b32 m0, s0
	v_readfirstlane_b32 s0, v2
	v_add_u32_e32 v2, 0x7000, v92
	v_lshl_add_u64 v[28:29], v[4:5], 0, v[26:27]
	v_lshlrev_b64 v[32:33], 11, v[32:33]
	global_load_lds_dwordx4 v[20:21], off
	s_mov_b32 m0, s0
	v_readfirstlane_b32 s0, v2
	v_lshl_add_u64 v[4:5], v[4:5], 0, v[32:33]
	global_load_lds_dwordx4 v[28:29], off
	s_mov_b32 m0, s0
	v_and_b32_e32 v87, 15, v34
	global_load_lds_dwordx4 v[4:5], off
	v_bfe_u32 v86, v34, 6, 1
	v_ashrrev_i32_e32 v88, 7, v34
	v_bfe_u32 v1, v34, 4, 2
	v_bfe_u32 v2, v34, 1, 3
	v_lshlrev_b32_e32 v3, 7, v87
	v_lshl_or_b32 v89, v88, 13, v3
	v_lshl_or_b32 v91, v86, 13, v3
	v_bitop3_b32 v3, v1, v2, 4 bitop3:0x36
	v_bitop3_b32 v2, v35, v2, 3 bitop3:0x6c
	v_lshlrev_b32_e32 v93, 4, v2
	v_bitop3_b32 v2, v35, 7, v34 bitop3:0x48
	v_lshlrev_b32_e32 v2, 4, v2
	v_readlane_b32 s0, v253, 13
	v_or_b32_e32 v10, v10, v2
	v_readlane_b32 s1, v253, 14
	v_or_b32_e32 v18, v18, v2
	v_or_b32_e32 v26, v26, v2
	v_or_b32_e32 v32, v32, v2
	s_waitcnt vmcnt(0)
	v_lshl_add_u64 v[66:67], s[0:1], 0, v[10:11]
	v_lshl_add_u64 v[68:69], s[0:1], 0, v[18:19]
	v_lshl_add_u64 v[70:71], s[0:1], 0, v[26:27]
	v_lshl_add_u64 v[72:73], s[0:1], 0, v[32:33]
	v_readlane_b32 s0, v254, 60
	v_or_b32_e32 v6, v6, v2
	v_readlane_b32 s1, v254, 61
	v_or_b32_e32 v14, v14, v2
	v_or_b32_e32 v22, v22, v2
	v_or_b32_e32 v30, v30, v2
	v_mov_b32_e32 v2, 0
	v_lshlrev_b32_e32 v90, 4, v3
	v_lshl_add_u64 v[74:75], s[0:1], 0, v[6:7]
	v_lshl_add_u64 v[76:77], s[0:1], 0, v[14:15]
	v_lshl_add_u64 v[78:79], s[0:1], 0, v[22:23]
	v_lshl_add_u64 v[80:81], s[0:1], 0, v[30:31]
	s_mov_b64 s[0:1], 0
	s_mov_b32 s28, 0x8000
	v_mov_b32_e32 v3, v2
	v_mov_b32_e32 v4, v2
	v_mov_b32_e32 v5, v2
	v_mov_b32_e32 v6, v2
	v_mov_b32_e32 v7, v2
	v_mov_b32_e32 v8, v2
	v_mov_b32_e32 v9, v2
	v_mov_b32_e32 v10, v2
	v_mov_b32_e32 v11, v2
	v_mov_b32_e32 v12, v2
	v_mov_b32_e32 v13, v2
	v_mov_b32_e32 v14, v2
	v_mov_b32_e32 v15, v2
	v_mov_b32_e32 v16, v2
	v_mov_b32_e32 v17, v2
	v_mov_b32_e32 v18, v2
	v_mov_b32_e32 v19, v2
	v_mov_b32_e32 v20, v2
	v_mov_b32_e32 v21, v2
	v_mov_b32_e32 v22, v2
	v_mov_b32_e32 v23, v2
	v_mov_b32_e32 v24, v2
	v_mov_b32_e32 v25, v2
	v_mov_b32_e32 v26, v2
	v_mov_b32_e32 v27, v2
	v_mov_b32_e32 v28, v2
	v_mov_b32_e32 v29, v2
	v_mov_b32_e32 v30, v2
	v_mov_b32_e32 v31, v2
	v_mov_b32_e32 v32, v2
	v_mov_b32_e32 v33, v2
	v_mov_b32_e32 v34, v2
	v_mov_b32_e32 v35, v2
	v_mov_b32_e32 v36, v2
	v_mov_b32_e32 v37, v2
	v_mov_b32_e32 v38, v2
	v_mov_b32_e32 v39, v2
	v_mov_b32_e32 v40, v2
	v_mov_b32_e32 v41, v2
	v_mov_b32_e32 v42, v2
	v_mov_b32_e32 v43, v2
	v_mov_b32_e32 v44, v2
	v_mov_b32_e32 v45, v2
	v_mov_b32_e32 v46, v2
	v_mov_b32_e32 v47, v2
	v_mov_b32_e32 v48, v2
	v_mov_b32_e32 v49, v2
	v_mov_b32_e32 v50, v2
	v_mov_b32_e32 v51, v2
	v_mov_b32_e32 v52, v2
	v_mov_b32_e32 v53, v2
	v_mov_b32_e32 v54, v2
	v_mov_b32_e32 v55, v2
	v_mov_b32_e32 v56, v2
	v_mov_b32_e32 v57, v2
	v_mov_b32_e32 v58, v2
	v_mov_b32_e32 v59, v2
	v_mov_b32_e32 v60, v2
	v_mov_b32_e32 v61, v2
	v_mov_b32_e32 v62, v2
	v_mov_b32_e32 v63, v2
	v_mov_b32_e32 v64, v2
	v_mov_b32_e32 v65, v2
	v_readlane_b32 s6, v253, 38
	v_readlane_b32 s7, v253, 39
	v_readlane_b32 s10, v253, 42
	v_readlane_b32 s11, v253, 43
	v_readlane_b32 s12, v253, 44
	v_readlane_b32 s13, v253, 45
	v_readlane_b32 s14, v253, 46
	v_readlane_b32 s15, v253, 47
	v_readlane_b32 s16, v253, 48
; #define LAS __attribute__((address_space(3)))
; template <class Epi>
; DI void gemm_tile(const bf16_t* __restrict__ A, int lda, const bf16_t* __restrict__ Bt, int ldb, int K, int row0, int col0, char* lds, const Epi& epi) {
;     ...
;   f32x4 acc[4][4];
; #pragma unroll
;   for (int m = 0; m < 4; ++m)
; #pragma unroll
;     for (int n = 0; n < 4; ++n) acc[m][n] = (f32x4){0.f, 0.f, 0.f, 0.f};
;   const int KT = K >> 6;
;   auto stage_a = [&](int kt, int buf) {
;     char* sa = lds + buf * 32768;
; #pragma unroll
;     for (int i = 0; i < 4; ++i)
;       __builtin_amdgcn_global_load_lds((const void __attribute__((address_space(1)))*)(ag[i] + kt * 64), (void LAS*)(sa + (i * 256 + tid) * 16), 16, 0, 0);
;   };
;   auto stage_b = [&](int kt, int buf) {
;     char* sb = lds + buf * 32768 + 16384;
; #pragma unroll
;     for (int i = 0; i < 4; ++i)
;       __builtin_amdgcn_global_load_lds((const void __attribute__((address_space(1)))*)(bg[i] + kt * 64), (void LAS*)(sb + (i * 256 + tid) * 16), 16, 0, 0);
;   };
;   __syncthreads();
;   stage_a(0, 0); stage_b(0, 0);
;   const int swz = fr >> 1;
;   for (int kt = 0; kt < KT; ++kt) {
;     asm volatile("s_waitcnt vmcnt(0)" ::: "memory");
;     __syncthreads();
;     const char* sa = lds + (kt & 1) * 32768 + (wr * 64 + fr) * 128;
;     const char* sb = lds + (kt & 1) * 32768 + 16384 + (wc * 64 + fr) * 128;
; #pragma unroll
;     for (int kk = 0; kk < 2; ++kk) {
;       if (kt + 1 < KT) { if (kk == 0) stage_a(kt + 1, (kt + 1) & 1); else stage_b(kt + 1, (kt + 1) & 1); }
;       bf16x8 a[4], b[4];
;       const int co = ((kk * 4 + fq) ^ swz) * 16;
; #pragma unroll
;       for (int m = 0; m < 4; ++m) a[m] = *(const bf16x8*)(sa + m * 2048 + co);
; #pragma unroll
;       for (int n = 0; n < 4; ++n) b[n] = *(const bf16x8*)(sb + n * 2048 + co);
; #pragma unroll
;       for (int m = 0; m < 4; ++m)
; #pragma unroll
;         for (int n = 0; n < 4; ++n) acc[m][n] = __builtin_amdgcn_mfma_f32_16x16x32_bf16(b[n], a[m], acc[m][n], 0, 0, 0);
	v_readlane_b32 s17, v253, 49
	v_readlane_b32 s18, v253, 50
	v_readlane_b32 s19, v253, 51
	v_mov_b32_e32 v162, 0
	v_mov_b32_e32 v163, 0
	v_mov_b32_e32 v164, 0
	v_mov_b32_e32 v165, 0
	v_mov_b32_e32 v166, 0
	v_mov_b32_e32 v167, 0
	v_mov_b32_e32 v168, 0
	v_mov_b32_e32 v169, 0
	v_mov_b32_e32 v170, 0
	v_mov_b32_e32 v171, 0
	v_mov_b32_e32 v172, 0
	v_mov_b32_e32 v173, 0
	v_mov_b32_e32 v174, 0
	v_mov_b32_e32 v175, 0
	v_mov_b32_e32 v176, 0
	v_mov_b32_e32 v177, 0
	v_mov_b32_e32 v178, 0
	v_mov_b32_e32 v179, 0
	v_mov_b32_e32 v180, 0
	v_mov_b32_e32 v181, 0
	v_mov_b32_e32 v182, 0
	v_mov_b32_e32 v183, 0
	v_mov_b32_e32 v184, 0
	v_mov_b32_e32 v185, 0
	v_mov_b32_e32 v186, 0
	v_mov_b32_e32 v187, 0
	v_mov_b32_e32 v188, 0
	v_mov_b32_e32 v189, 0
	v_mov_b32_e32 v190, 0
	v_mov_b32_e32 v191, 0
	v_mov_b32_e32 v192, 0
	v_mov_b32_e32 v193, 0
	v_mov_b32_e32 v194, 0
	v_mov_b32_e32 v195, 0
	v_mov_b32_e32 v196, 0
	v_mov_b32_e32 v197, 0
	v_mov_b32_e32 v198, 0
	v_mov_b32_e32 v199, 0
	v_mov_b32_e32 v200, 0
	v_mov_b32_e32 v201, 0
	v_mov_b32_e32 v202, 0
	v_mov_b32_e32 v203, 0
	v_mov_b32_e32 v204, 0
	v_mov_b32_e32 v205, 0
	v_mov_b32_e32 v206, 0
	v_mov_b32_e32 v207, 0
	v_mov_b32_e32 v208, 0
	v_mov_b32_e32 v209, 0
	v_mov_b32_e32 v210, 0
	v_mov_b32_e32 v211, 0
	v_mov_b32_e32 v212, 0
	v_mov_b32_e32 v213, 0
	v_mov_b32_e32 v214, 0
	v_mov_b32_e32 v215, 0
	v_mov_b32_e32 v216, 0
	v_mov_b32_e32 v217, 0
	v_mov_b32_e32 v218, 0
	v_mov_b32_e32 v219, 0
	v_mov_b32_e32 v220, 0
	v_mov_b32_e32 v221, 0
	v_mov_b32_e32 v222, 0
	v_mov_b32_e32 v223, 0
	v_mov_b32_e32 v224, 0
	v_mov_b32_e32 v225, 0
	v_readfirstlane_b32 s21, v92
	v_add_u32_e32 v242, v89, v93
	v_add_u32_e32 v243, v91, v93
	v_add_u32_e32 v244, v89, v90
	v_add_u32_e32 v245, v91, v90
	s_mov_b32 s0, 0x3ff80
	s_mov_b32 s1, 0
	s_add_i32 m0, s21, 0x8000
	v_lshl_add_u64 v[82:83], v[74:75], 0, s[0:1]
	global_load_lds_dwordx4 v[82:83], off
	s_add_i32 m0, m0, 0x1000
	v_lshl_add_u64 v[82:83], v[76:77], 0, s[0:1]
	global_load_lds_dwordx4 v[82:83], off
	s_add_i32 m0, m0, 0x1000
	v_lshl_add_u64 v[82:83], v[78:79], 0, s[0:1]
	global_load_lds_dwordx4 v[82:83], off
	s_add_i32 m0, m0, 0x1000
	v_lshl_add_u64 v[82:83], v[80:81], 0, s[0:1]
	global_load_lds_dwordx4 v[82:83], off
	s_mov_b64 s[0:1], 0
	s_add_i32 m0, s21, 0xc000
	v_lshl_add_u64 v[82:83], v[66:67], 0, s[0:1]
	global_load_lds_dwordx4 v[82:83], off
	s_add_i32 m0, m0, 0x1000
	v_lshl_add_u64 v[82:83], v[68:69], 0, s[0:1]
	global_load_lds_dwordx4 v[82:83], off
	s_add_i32 m0, m0, 0x1000
	v_lshl_add_u64 v[82:83], v[70:71], 0, s[0:1]
	global_load_lds_dwordx4 v[82:83], off
	s_add_i32 m0, m0, 0x1000
	v_lshl_add_u64 v[82:83], v[72:73], 0, s[0:1]
	global_load_lds_dwordx4 v[82:83], off
.LBB0_136:
	s_waitcnt vmcnt(0)
	s_barrier
	s_cmpk_eq_i32 s0, 0
	s_cbranch_scc1 .Lffi4_nob0
	s_add_i32 m0, s21, 0xc000
	v_lshl_add_u64 v[82:83], v[66:67], 0, s[0:1]
	global_load_lds_dwordx4 v[82:83], off
	s_add_i32 m0, m0, 0x1000
	v_lshl_add_u64 v[84:85], v[68:69], 0, s[0:1]
	global_load_lds_dwordx4 v[84:85], off
	s_add_i32 m0, m0, 0x1000
	v_lshl_add_u64 v[82:83], v[70:71], 0, s[0:1]
	global_load_lds_dwordx4 v[82:83], off
	s_add_i32 m0, m0, 0x1000
	v_lshl_add_u64 v[84:85], v[72:73], 0, s[0:1]
	global_load_lds_dwordx4 v[84:85], off
.Lffi4_nob0:
	ds_read_b128 v[94:97], v242
	ds_read_b128 v[98:101], v242 offset:2048
	ds_read_b128 v[102:105], v242 offset:4096
	ds_read_b128 v[106:109], v242 offset:6144
	ds_read_b128 v[116:119], v243 offset:16384
	ds_read_b128 v[120:123], v243 offset:18432
	ds_read_b128 v[124:127], v243 offset:20480
	ds_read_b128 v[128:131], v243 offset:22528
	ds_read_b128 v[226:229], v242 offset:32768
	ds_read_b128 v[230:233], v242 offset:34816
	ds_read_b128 v[234:237], v242 offset:36864
	ds_read_b128 v[238:241], v242 offset:38912
	s_waitcnt lgkmcnt(0)
	v_mfma_f32_16x16x32_bf16 v[62:65], v[116:119], v[94:97], v[62:65]
	v_mfma_f32_16x16x32_bf16 v[58:61], v[120:123], v[94:97], v[58:61]
	v_mfma_f32_16x16x32_bf16 v[54:57], v[124:127], v[94:97], v[54:57]
	v_mfma_f32_16x16x32_bf16 v[50:53], v[128:131], v[94:97], v[50:53]
	v_mfma_f32_16x16x32_bf16 v[46:49], v[116:119], v[98:101], v[46:49]
	v_mfma_f32_16x16x32_bf16 v[42:45], v[120:123], v[98:101], v[42:45]
	v_mfma_f32_16x16x32_bf16 v[38:41], v[124:127], v[98:101], v[38:41]
	v_mfma_f32_16x16x32_bf16 v[34:37], v[128:131], v[98:101], v[34:37]
	v_mfma_f32_16x16x32_bf16 v[30:33], v[116:119], v[102:105], v[30:33]
	v_mfma_f32_16x16x32_bf16 v[26:29], v[120:123], v[102:105], v[26:29]
	v_mfma_f32_16x16x32_bf16 v[22:25], v[124:127], v[102:105], v[22:25]
	v_mfma_f32_16x16x32_bf16 v[18:21], v[128:131], v[102:105], v[18:21]
	v_mfma_f32_16x16x32_bf16 v[14:17], v[116:119], v[106:109], v[14:17]
	v_mfma_f32_16x16x32_bf16 v[10:13], v[120:123], v[106:109], v[10:13]
	v_mfma_f32_16x16x32_bf16 v[6:9], v[124:127], v[106:109], v[6:9]
	v_mfma_f32_16x16x32_bf16 v[2:5], v[128:131], v[106:109], v[2:5]
	v_mfma_f32_16x16x32_bf16 v[222:225], v[116:119], v[226:229], v[222:225]
	v_mfma_f32_16x16x32_bf16 v[218:221], v[120:123], v[226:229], v[218:221]
	v_mfma_f32_16x16x32_bf16 v[214:217], v[124:127], v[226:229], v[214:217]
	v_mfma_f32_16x16x32_bf16 v[210:213], v[128:131], v[226:229], v[210:213]
	v_mfma_f32_16x16x32_bf16 v[206:209], v[116:119], v[230:233], v[206:209]
	v_mfma_f32_16x16x32_bf16 v[202:205], v[120:123], v[230:233], v[202:205]
	v_mfma_f32_16x16x32_bf16 v[198:201], v[124:127], v[230:233], v[198:201]
	v_mfma_f32_16x16x32_bf16 v[194:197], v[128:131], v[230:233], v[194:197]
	v_mfma_f32_16x16x32_bf16 v[190:193], v[116:119], v[234:237], v[190:193]
	v_mfma_f32_16x16x32_bf16 v[186:189], v[120:123], v[234:237], v[186:189]
	v_mfma_f32_16x16x32_bf16 v[182:185], v[124:127], v[234:237], v[182:185]
	v_mfma_f32_16x16x32_bf16 v[178:181], v[128:131], v[234:237], v[178:181]
	v_mfma_f32_16x16x32_bf16 v[174:177], v[116:119], v[238:241], v[174:177]
	v_mfma_f32_16x16x32_bf16 v[170:173], v[120:123], v[238:241], v[170:173]
	v_mfma_f32_16x16x32_bf16 v[166:169], v[124:127], v[238:241], v[166:169]
	v_mfma_f32_16x16x32_bf16 v[162:165], v[128:131], v[238:241], v[162:165]
	ds_read_b128 v[94:97], v244
	ds_read_b128 v[98:101], v244 offset:2048
	ds_read_b128 v[102:105], v244 offset:4096
	ds_read_b128 v[106:109], v244 offset:6144
	ds_read_b128 v[116:119], v245 offset:16384
	ds_read_b128 v[120:123], v245 offset:18432
	ds_read_b128 v[124:127], v245 offset:20480
	ds_read_b128 v[128:131], v245 offset:22528
	ds_read_b128 v[226:229], v244 offset:32768
	ds_read_b128 v[230:233], v244 offset:34816
	ds_read_b128 v[234:237], v244 offset:36864
	ds_read_b128 v[238:241], v244 offset:38912
	s_waitcnt lgkmcnt(0)
	s_barrier
; template <class Epi>
; DI void gemm_tile(const bf16_t* __restrict__ A, int lda, const bf16_t* __restrict__ Bt, int ldb, int K, int row0, int col0, char* lds, const Epi& epi) {
;     ...
;   for (int kt = 0; kt < KT; ++kt) {
;     asm volatile("s_waitcnt vmcnt(0)" ::: "memory");
;     __syncthreads();
;     const char* sa = lds + (kt & 1) * 32768 + (wr * 64 + fr) * 128;
;     const char* sb = lds + (kt & 1) * 32768 + 16384 + (wc * 64 + fr) * 128;
; #pragma unroll
;     for (int kk = 0; kk < 2; ++kk) {
;       if (kt + 1 < KT) { if (kk == 0) stage_a(kt + 1, (kt + 1) & 1); else stage_b(kt + 1, (kt + 1) & 1); }
;       bf16x8 a[4], b[4];
;       const int co = ((kk * 4 + fq) ^ swz) * 16;
; #pragma unroll
;       for (int m = 0; m < 4; ++m) a[m] = *(const bf16x8*)(sa + m * 2048 + co);
; #pragma unroll
;       for (int n = 0; n < 4; ++n) b[n] = *(const bf16x8*)(sb + n * 2048 + co);
; #pragma unroll
;       for (int m = 0; m < 4; ++m)
; #pragma unroll
;         for (int n = 0; n < 4; ++n) acc[m][n] = __builtin_amdgcn_mfma_f32_16x16x32_bf16(b[n], a[m], acc[m][n], 0, 0, 0);
	s_mov_b32 m0, s21
	v_lshl_add_u64 v[82:83], v[74:75], 0, s[0:1]
	global_load_lds_dwordx4 v[82:83], off
	s_add_i32 m0, m0, 0x1000
	v_lshl_add_u64 v[84:85], v[76:77], 0, s[0:1]
	global_load_lds_dwordx4 v[84:85], off
	s_add_i32 m0, m0, 0x1000
	v_lshl_add_u64 v[82:83], v[78:79], 0, s[0:1]
	global_load_lds_dwordx4 v[82:83], off
	s_add_i32 m0, m0, 0x1000
	v_lshl_add_u64 v[84:85], v[80:81], 0, s[0:1]
	global_load_lds_dwordx4 v[84:85], off
	s_add_i32 m0, m0, 0x1000
	s_add_u32 s20, s0, 0x40000
	s_add_i32 m0, s21, 0x8000
	v_add_co_u32_e32 v82, vcc, s20, v74
	v_addc_co_u32_e32 v83, vcc, 0, v75, vcc
	global_load_lds_dwordx4 v[82:83], off
	s_add_i32 m0, m0, 0x1000
	v_add_co_u32_e32 v84, vcc, s20, v76
	v_addc_co_u32_e32 v85, vcc, 0, v77, vcc
	global_load_lds_dwordx4 v[84:85], off
	s_add_i32 m0, m0, 0x1000
	v_add_co_u32_e32 v82, vcc, s20, v78
	v_addc_co_u32_e32 v83, vcc, 0, v79, vcc
	global_load_lds_dwordx4 v[82:83], off
	s_add_i32 m0, m0, 0x1000
	v_add_co_u32_e32 v84, vcc, s20, v80
	v_addc_co_u32_e32 v85, vcc, 0, v81, vcc
	global_load_lds_dwordx4 v[84:85], off
	v_mfma_f32_16x16x32_bf16 v[62:65], v[116:119], v[94:97], v[62:65]
	v_mfma_f32_16x16x32_bf16 v[58:61], v[120:123], v[94:97], v[58:61]
	v_mfma_f32_16x16x32_bf16 v[54:57], v[124:127], v[94:97], v[54:57]
	v_mfma_f32_16x16x32_bf16 v[50:53], v[128:131], v[94:97], v[50:53]
	v_mfma_f32_16x16x32_bf16 v[46:49], v[116:119], v[98:101], v[46:49]
	v_mfma_f32_16x16x32_bf16 v[42:45], v[120:123], v[98:101], v[42:45]
	v_mfma_f32_16x16x32_bf16 v[38:41], v[124:127], v[98:101], v[38:41]
	v_mfma_f32_16x16x32_bf16 v[34:37], v[128:131], v[98:101], v[34:37]
	v_mfma_f32_16x16x32_bf16 v[30:33], v[116:119], v[102:105], v[30:33]
	v_mfma_f32_16x16x32_bf16 v[26:29], v[120:123], v[102:105], v[26:29]
	v_mfma_f32_16x16x32_bf16 v[22:25], v[124:127], v[102:105], v[22:25]
	v_mfma_f32_16x16x32_bf16 v[18:21], v[128:131], v[102:105], v[18:21]
	v_mfma_f32_16x16x32_bf16 v[14:17], v[116:119], v[106:109], v[14:17]
	v_mfma_f32_16x16x32_bf16 v[10:13], v[120:123], v[106:109], v[10:13]
	v_mfma_f32_16x16x32_bf16 v[6:9], v[124:127], v[106:109], v[6:9]
	v_mfma_f32_16x16x32_bf16 v[2:5], v[128:131], v[106:109], v[2:5]
	v_mfma_f32_16x16x32_bf16 v[222:225], v[116:119], v[226:229], v[222:225]
	v_mfma_f32_16x16x32_bf16 v[218:221], v[120:123], v[226:229], v[218:221]
	v_mfma_f32_16x16x32_bf16 v[214:217], v[124:127], v[226:229], v[214:217]
	v_mfma_f32_16x16x32_bf16 v[210:213], v[128:131], v[226:229], v[210:213]
	v_mfma_f32_16x16x32_bf16 v[206:209], v[116:119], v[230:233], v[206:209]
	v_mfma_f32_16x16x32_bf16 v[202:205], v[120:123], v[230:233], v[202:205]
	v_mfma_f32_16x16x32_bf16 v[198:201], v[124:127], v[230:233], v[198:201]
	v_mfma_f32_16x16x32_bf16 v[194:197], v[128:131], v[230:233], v[194:197]
	v_mfma_f32_16x16x32_bf16 v[190:193], v[116:119], v[234:237], v[190:193]
	v_mfma_f32_16x16x32_bf16 v[186:189], v[120:123], v[234:237], v[186:189]
	v_mfma_f32_16x16x32_bf16 v[182:185], v[124:127], v[234:237], v[182:185]
	v_mfma_f32_16x16x32_bf16 v[178:181], v[128:131], v[234:237], v[178:181]
	v_mfma_f32_16x16x32_bf16 v[174:177], v[116:119], v[238:241], v[174:177]
	v_mfma_f32_16x16x32_bf16 v[170:173], v[120:123], v[238:241], v[170:173]
	v_mfma_f32_16x16x32_bf16 v[166:169], v[124:127], v[238:241], v[166:169]
	v_mfma_f32_16x16x32_bf16 v[162:165], v[128:131], v[238:241], v[162:165]
	s_add_u32 s0, s0, 0x80
	s_waitcnt vmcnt(0)
	s_barrier
	s_cmpk_eq_i32 s0, 0x780
	s_cbranch_scc1 .Lffi4_nob1
	s_add_i32 m0, s21, 0x4000
	v_lshl_add_u64 v[82:83], v[66:67], 0, s[0:1]
	global_load_lds_dwordx4 v[82:83], off
	s_add_i32 m0, m0, 0x1000
	v_lshl_add_u64 v[84:85], v[68:69], 0, s[0:1]
	global_load_lds_dwordx4 v[84:85], off
	s_add_i32 m0, m0, 0x1000
	v_lshl_add_u64 v[82:83], v[70:71], 0, s[0:1]
	global_load_lds_dwordx4 v[82:83], off
	s_add_i32 m0, m0, 0x1000
	v_lshl_add_u64 v[84:85], v[72:73], 0, s[0:1]
	global_load_lds_dwordx4 v[84:85], off
; template <class Epi>
; DI void gemm_tile(const bf16_t* __restrict__ A, int lda, const bf16_t* __restrict__ Bt, int ldb, int K, int row0, int col0, char* lds, const Epi& epi) {
;     ...
;   for (int kt = 0; kt < KT; ++kt) {
;     asm volatile("s_waitcnt vmcnt(0)" ::: "memory");
;     __syncthreads();
;     const char* sa = lds + (kt & 1) * 32768 + (wr * 64 + fr) * 128;
;     const char* sb = lds + (kt & 1) * 32768 + 16384 + (wc * 64 + fr) * 128;
; #pragma unroll
;     for (int kk = 0; kk < 2; ++kk) {
;       if (kt + 1 < KT) { if (kk == 0) stage_a(kt + 1, (kt + 1) & 1); else stage_b(kt + 1, (kt + 1) & 1); }
;       bf16x8 a[4], b[4];
;       const int co = ((kk * 4 + fq) ^ swz) * 16;
; #pragma unroll
;       for (int m = 0; m < 4; ++m) a[m] = *(const bf16x8*)(sa + m * 2048 + co);
; #pragma unroll
;       for (int n = 0; n < 4; ++n) b[n] = *(const bf16x8*)(sb + n * 2048 + co);
; #pragma unroll
;       for (int m = 0; m < 4; ++m)
; #pragma unroll
;         for (int n = 0; n < 4; ++n) acc[m][n] = __builtin_amdgcn_mfma_f32_16x16x32_bf16(b[n], a[m], acc[m][n], 0, 0, 0);
.Lffi4_nob1:
	ds_read_b128 v[94:97], v242
	ds_read_b128 v[98:101], v242 offset:2048
	ds_read_b128 v[102:105], v242 offset:4096
	ds_read_b128 v[106:109], v242 offset:6144
	ds_read_b128 v[116:119], v243 offset:49152
	ds_read_b128 v[120:123], v243 offset:51200
	ds_read_b128 v[124:127], v243 offset:53248
	ds_read_b128 v[128:131], v243 offset:55296
	ds_read_b128 v[226:229], v242 offset:32768
	ds_read_b128 v[230:233], v242 offset:34816
	ds_read_b128 v[234:237], v242 offset:36864
	ds_read_b128 v[238:241], v242 offset:38912
	s_waitcnt lgkmcnt(0)
	v_mfma_f32_16x16x32_bf16 v[62:65], v[116:119], v[94:97], v[62:65]
	v_mfma_f32_16x16x32_bf16 v[58:61], v[120:123], v[94:97], v[58:61]
	v_mfma_f32_16x16x32_bf16 v[54:57], v[124:127], v[94:97], v[54:57]
	v_mfma_f32_16x16x32_bf16 v[50:53], v[128:131], v[94:97], v[50:53]
	v_mfma_f32_16x16x32_bf16 v[46:49], v[116:119], v[98:101], v[46:49]
	v_mfma_f32_16x16x32_bf16 v[42:45], v[120:123], v[98:101], v[42:45]
	v_mfma_f32_16x16x32_bf16 v[38:41], v[124:127], v[98:101], v[38:41]
	v_mfma_f32_16x16x32_bf16 v[34:37], v[128:131], v[98:101], v[34:37]
	v_mfma_f32_16x16x32_bf16 v[30:33], v[116:119], v[102:105], v[30:33]
	v_mfma_f32_16x16x32_bf16 v[26:29], v[120:123], v[102:105], v[26:29]
	v_mfma_f32_16x16x32_bf16 v[22:25], v[124:127], v[102:105], v[22:25]
	v_mfma_f32_16x16x32_bf16 v[18:21], v[128:131], v[102:105], v[18:21]
	v_mfma_f32_16x16x32_bf16 v[14:17], v[116:119], v[106:109], v[14:17]
	v_mfma_f32_16x16x32_bf16 v[10:13], v[120:123], v[106:109], v[10:13]
	v_mfma_f32_16x16x32_bf16 v[6:9], v[124:127], v[106:109], v[6:9]
	v_mfma_f32_16x16x32_bf16 v[2:5], v[128:131], v[106:109], v[2:5]
	v_mfma_f32_16x16x32_bf16 v[222:225], v[116:119], v[226:229], v[222:225]
	v_mfma_f32_16x16x32_bf16 v[218:221], v[120:123], v[226:229], v[218:221]
	v_mfma_f32_16x16x32_bf16 v[214:217], v[124:127], v[226:229], v[214:217]
	v_mfma_f32_16x16x32_bf16 v[210:213], v[128:131], v[226:229], v[210:213]
	v_mfma_f32_16x16x32_bf16 v[206:209], v[116:119], v[230:233], v[206:209]
	v_mfma_f32_16x16x32_bf16 v[202:205], v[120:123], v[230:233], v[202:205]
	v_mfma_f32_16x16x32_bf16 v[198:201], v[124:127], v[230:233], v[198:201]
	v_mfma_f32_16x16x32_bf16 v[194:197], v[128:131], v[230:233], v[194:197]
	v_mfma_f32_16x16x32_bf16 v[190:193], v[116:119], v[234:237], v[190:193]
	v_mfma_f32_16x16x32_bf16 v[186:189], v[120:123], v[234:237], v[186:189]
	v_mfma_f32_16x16x32_bf16 v[182:185], v[124:127], v[234:237], v[182:185]
	v_mfma_f32_16x16x32_bf16 v[178:181], v[128:131], v[234:237], v[178:181]
	v_mfma_f32_16x16x32_bf16 v[174:177], v[116:119], v[238:241], v[174:177]
	v_mfma_f32_16x16x32_bf16 v[170:173], v[120:123], v[238:241], v[170:173]
	v_mfma_f32_16x16x32_bf16 v[166:169], v[124:127], v[238:241], v[166:169]
	v_mfma_f32_16x16x32_bf16 v[162:165], v[128:131], v[238:241], v[162:165]
	ds_read_b128 v[94:97], v244
	ds_read_b128 v[98:101], v244 offset:2048
	ds_read_b128 v[102:105], v244 offset:4096
	ds_read_b128 v[106:109], v244 offset:6144
	ds_read_b128 v[116:119], v245 offset:49152
	ds_read_b128 v[120:123], v245 offset:51200
	ds_read_b128 v[124:127], v245 offset:53248
	ds_read_b128 v[128:131], v245 offset:55296
	ds_read_b128 v[226:229], v244 offset:32768
	ds_read_b128 v[230:233], v244 offset:34816
	ds_read_b128 v[234:237], v244 offset:36864
	ds_read_b128 v[238:241], v244 offset:38912
	s_waitcnt lgkmcnt(0)
	s_barrier
	s_cmpk_eq_i32 s0, 0x780
	s_cbranch_scc1 .Lffi4_noa
	s_mov_b32 m0, s21
	v_lshl_add_u64 v[82:83], v[74:75], 0, s[0:1]
	global_load_lds_dwordx4 v[82:83], off
	s_add_i32 m0, m0, 0x1000
	v_lshl_add_u64 v[84:85], v[76:77], 0, s[0:1]
	global_load_lds_dwordx4 v[84:85], off
	s_add_i32 m0, m0, 0x1000
	v_lshl_add_u64 v[82:83], v[78:79], 0, s[0:1]
	global_load_lds_dwordx4 v[82:83], off
	s_add_i32 m0, m0, 0x1000
	v_lshl_add_u64 v[84:85], v[80:81], 0, s[0:1]
	global_load_lds_dwordx4 v[84:85], off
	s_add_i32 m0, m0, 0x1000
	s_add_u32 s20, s0, 0x40000
	s_add_i32 m0, s21, 0x8000
	v_add_co_u32_e32 v82, vcc, s20, v74
	v_addc_co_u32_e32 v83, vcc, 0, v75, vcc
	global_load_lds_dwordx4 v[82:83], off
	s_add_i32 m0, m0, 0x1000
	v_add_co_u32_e32 v84, vcc, s20, v76
	v_addc_co_u32_e32 v85, vcc, 0, v77, vcc
	global_load_lds_dwordx4 v[84:85], off
	s_add_i32 m0, m0, 0x1000
	v_add_co_u32_e32 v82, vcc, s20, v78
	v_addc_co_u32_e32 v83, vcc, 0, v79, vcc
	global_load_lds_dwordx4 v[82:83], off
	s_add_i32 m0, m0, 0x1000
	v_add_co_u32_e32 v84, vcc, s20, v80
	v_addc_co_u32_e32 v85, vcc, 0, v81, vcc
	global_load_lds_dwordx4 v[84:85], off
